# v13 + phase-9 cross-attention epilogue stores widened to dwordx4 via permlane32_swap (8 stores per wave instead of 16)
# baseline (speedup 1.0000x reference)
; #define LAS __attribute__((address_space(3)))
; __device__ __forceinline__ int queue_next(unsigned* ctr, LAS unsigned char* lds) {
;     volatile LAS unsigned* w = (volatile LAS unsigned*)(lds + LDS_CTL);
;     if (threadIdx.x == 0) w[0] = atomicAdd(ctr, 1u);
;     __syncthreads();
;     const int u = (int)w[0];
;     __syncthreads();
;     return u;
; }
; __global__ void __launch_bounds__(512, 2) mega(Params p) {
;     ...
;             for (;;) {
;                 int u = queue_next(ctr, lds);
;                 if (u >= NU_P + NU_S) break;
;                 if (u < NU_P) cross_unit(p, lds, u >> 6, (u >> 4) & 3, u & 15);
.LBB0_1324:
	s_waitcnt lgkmcnt(0)
	s_mov_b64 s[16:17], exec
	v_readlane_b32 s18, v252, 6
	v_readlane_b32 s19, v252, 7
	s_and_b64 s[18:19], s[16:17], s[18:19]
	s_mov_b64 exec, s[18:19]
	s_cbranch_execz .LBB0_1326
	s_waitcnt vmcnt(8)
	v_mov_b32_e32 v2, s0
	ds_write_b32 v2, v250

; #define GASP __attribute__((address_space(1)))
; __device__ __forceinline__ float frcp(float x) { return __builtin_amdgcn_rcpf(x); }
; __device__ __forceinline__ void cross_unit(const Params& p, LAS unsigned char* L, int bb, int h, int qi) {
;     ...
;     if (active) {
;         l += __shfl_xor(l, 32);
;         const float inv = frcp(l);
;         bf16_t* op = (bf16_t*)(ws + O_OC) + (size_t)(rowq0 + sub * 32 + r) * D + h * 256 + dh * 128 + 4 * hi;
; #pragma unroll
;         for (int eb = 0; eb < 4; ++eb)
; #pragma unroll
;             for (int g4 = 0; g4 < 4; ++g4) { u32x2 w; w.x = pk2(OT[eb][4 * g4] * inv, OT[eb][4 * g4 + 1] * inv); w.y = pk2(OT[eb][4 * g4 + 2] * inv, OT[eb][4 * g4 + 3] * inv);
;                 *(GASP u32x2*)(op + eb * 32 + 8 * g4) = w; }
;     }
.Lq9_pf_done:
	s_mov_b64 exec, s[100:101]
	s_waitcnt lgkmcnt(0)
	v_add_f32_e32 v0, v213, v0
	v_rcp_f32_e32 v0, v0
	v_ashrrev_i32_e32 v2, 1, v2
	v_lshl_add_u64 v[4:5], s[12:13], 0, v[210:211]
	v_and_b32_e32 v2, 0xffffff80, v2
	v_lshl_add_u64 v[4:5], s[14:15], 1, v[4:5]
	v_ashrrev_i32_e32 v3, 31, v2
	v_lshl_add_u64 v[2:3], v[2:3], 1, v[4:5]
	v_mov_b32_e32 v213, v1
	v_mbcnt_lo_u32_b32 v6, -1, 0
	v_mbcnt_hi_u32_b32 v6, -1, v6
	v_and_b32_e32 v6, 32, v6
	v_lshrrev_b32_e32 v6, 2, v6
	s_waitcnt vmcnt(4)
	v_lshl_add_u64 v[2:3], v[212:213], 1, v[2:3]
	v_add_co_u32_e32 v2, vcc, v6, v2
	s_nop 1
	v_addc_co_u32_e32 v3, vcc, 0, v3, vcc
	v_pk_mul_f32 v[4:5], v[64:65], v[0:1] op_sel_hi:[1,0]
	v_pk_mul_f32 v[6:7], v[66:67], v[0:1] op_sel_hi:[1,0]
	v_cvt_pk_bf16_f32 v242, v4, v5
	v_cvt_pk_bf16_f32 v243, v6, v7
	v_pk_mul_f32 v[4:5], v[68:69], v[0:1] op_sel_hi:[1,0]
	v_pk_mul_f32 v[6:7], v[70:71], v[0:1] op_sel_hi:[1,0]
	v_cvt_pk_bf16_f32 v244, v4, v5
	v_cvt_pk_bf16_f32 v245, v6, v7
	s_nop 1
	v_permlane32_swap_b32_e32 v242, v244
	v_permlane32_swap_b32_e32 v243, v245
	global_store_dwordx4 v[2:3], v[242:245], off
	v_pk_mul_f32 v[4:5], v[72:73], v[0:1] op_sel_hi:[1,0]
	v_pk_mul_f32 v[6:7], v[74:75], v[0:1] op_sel_hi:[1,0]
	v_cvt_pk_bf16_f32 v246, v4, v5
	v_cvt_pk_bf16_f32 v247, v6, v7
	v_pk_mul_f32 v[4:5], v[76:77], v[0:1] op_sel_hi:[1,0]
	v_pk_mul_f32 v[6:7], v[78:79], v[0:1] op_sel_hi:[1,0]
	v_cvt_pk_bf16_f32 v248, v4, v5
	v_cvt_pk_bf16_f32 v249, v6, v7
	s_nop 1
	v_permlane32_swap_b32_e32 v246, v248
	v_permlane32_swap_b32_e32 v247, v249
	global_store_dwordx4 v[2:3], v[246:249], off offset:32
	v_pk_mul_f32 v[4:5], v[48:49], v[0:1] op_sel_hi:[1,0]
	v_pk_mul_f32 v[6:7], v[50:51], v[0:1] op_sel_hi:[1,0]
	v_cvt_pk_bf16_f32 v242, v4, v5
	v_cvt_pk_bf16_f32 v243, v6, v7
	v_pk_mul_f32 v[4:5], v[52:53], v[0:1] op_sel_hi:[1,0]
	v_pk_mul_f32 v[6:7], v[54:55], v[0:1] op_sel_hi:[1,0]
	v_cvt_pk_bf16_f32 v244, v4, v5
	v_cvt_pk_bf16_f32 v245, v6, v7
	s_nop 1
	v_permlane32_swap_b32_e32 v242, v244
	v_permlane32_swap_b32_e32 v243, v245
	global_store_dwordx4 v[2:3], v[242:245], off offset:64
	v_pk_mul_f32 v[4:5], v[56:57], v[0:1] op_sel_hi:[1,0]
	v_pk_mul_f32 v[6:7], v[58:59], v[0:1] op_sel_hi:[1,0]
	v_cvt_pk_bf16_f32 v246, v4, v5
	v_cvt_pk_bf16_f32 v247, v6, v7
	v_pk_mul_f32 v[4:5], v[60:61], v[0:1] op_sel_hi:[1,0]
	v_pk_mul_f32 v[6:7], v[62:63], v[0:1] op_sel_hi:[1,0]
	v_cvt_pk_bf16_f32 v248, v4, v5
	v_cvt_pk_bf16_f32 v249, v6, v7
	s_nop 1
	v_permlane32_swap_b32_e32 v246, v248
	v_permlane32_swap_b32_e32 v247, v249
	global_store_dwordx4 v[2:3], v[246:249], off offset:96
	v_pk_mul_f32 v[4:5], v[32:33], v[0:1] op_sel_hi:[1,0]
	v_pk_mul_f32 v[6:7], v[34:35], v[0:1] op_sel_hi:[1,0]
	v_cvt_pk_bf16_f32 v242, v4, v5
	v_cvt_pk_bf16_f32 v243, v6, v7
	v_pk_mul_f32 v[4:5], v[36:37], v[0:1] op_sel_hi:[1,0]
	v_pk_mul_f32 v[6:7], v[38:39], v[0:1] op_sel_hi:[1,0]
	v_cvt_pk_bf16_f32 v244, v4, v5
	v_cvt_pk_bf16_f32 v245, v6, v7
	s_nop 1
	v_permlane32_swap_b32_e32 v242, v244
	v_permlane32_swap_b32_e32 v243, v245
	global_store_dwordx4 v[2:3], v[242:245], off offset:128
	v_pk_mul_f32 v[4:5], v[40:41], v[0:1] op_sel_hi:[1,0]
	v_pk_mul_f32 v[6:7], v[42:43], v[0:1] op_sel_hi:[1,0]
	v_cvt_pk_bf16_f32 v246, v4, v5
	v_cvt_pk_bf16_f32 v247, v6, v7
	v_pk_mul_f32 v[4:5], v[44:45], v[0:1] op_sel_hi:[1,0]
	v_pk_mul_f32 v[6:7], v[46:47], v[0:1] op_sel_hi:[1,0]
	v_cvt_pk_bf16_f32 v248, v4, v5
	v_cvt_pk_bf16_f32 v249, v6, v7
	s_nop 1
	v_permlane32_swap_b32_e32 v246, v248
	v_permlane32_swap_b32_e32 v247, v249
	global_store_dwordx4 v[2:3], v[246:249], off offset:160
	v_pk_mul_f32 v[4:5], v[16:17], v[0:1] op_sel_hi:[1,0]
	v_pk_mul_f32 v[6:7], v[18:19], v[0:1] op_sel_hi:[1,0]
	v_cvt_pk_bf16_f32 v242, v4, v5
	v_cvt_pk_bf16_f32 v243, v6, v7
	v_pk_mul_f32 v[4:5], v[20:21], v[0:1] op_sel_hi:[1,0]
	v_pk_mul_f32 v[6:7], v[22:23], v[0:1] op_sel_hi:[1,0]
	v_cvt_pk_bf16_f32 v244, v4, v5
	v_cvt_pk_bf16_f32 v245, v6, v7
	s_nop 1
	v_permlane32_swap_b32_e32 v242, v244
	v_permlane32_swap_b32_e32 v243, v245
	global_store_dwordx4 v[2:3], v[242:245], off offset:192
	v_pk_mul_f32 v[4:5], v[24:25], v[0:1] op_sel_hi:[1,0]
	v_pk_mul_f32 v[6:7], v[26:27], v[0:1] op_sel_hi:[1,0]
	v_cvt_pk_bf16_f32 v246, v4, v5
	v_cvt_pk_bf16_f32 v247, v6, v7
	v_pk_mul_f32 v[4:5], v[28:29], v[0:1] op_sel_hi:[1,0]
	v_pk_mul_f32 v[6:7], v[30:31], v[0:1] op_sel_hi:[1,0]
	v_cvt_pk_bf16_f32 v248, v4, v5
	v_cvt_pk_bf16_f32 v249, v6, v7
	s_nop 1
	v_permlane32_swap_b32_e32 v246, v248
	v_permlane32_swap_b32_e32 v247, v249
	global_store_dwordx4 v[2:3], v[246:249], off offset:224
	s_branch .LBB0_1322
